# dwconv register window: incremental tiles wait vmcnt(8) (prefetch loads only, not the LayerNorm stores)
# baseline (speedup 1.0000x reference)
; #define LAS __attribute__((address_space(3)))
; __global__ void __launch_bounds__(512, 2) fwd_kernel(Args a) {
;     ...
;             {
;                 u32x4 sv[12];
; #pragma unroll
;                 for (int k = 0; k < 12; ++k) { const int gi = tid + 512 * k, rr = gi >> 7, cc = gi & 127; const int t = t0 - 30 + rr;
;                     sv[k] = (u32x4){0u, 0u, 0u, 0u}; if (gi < 46 * 128 && t >= 0 && t < LSEQ) sv[k] = *(const u32x4*)(BIG + (rb + t) * DM + cc * 8); }
; #pragma unroll
;                 for (int k = 0; k < 12; ++k) { const int gi = tid + 512 * k, rr = gi >> 7, cc = gi & 127; if (gi < 46 * 128) *(LAS u32x4*)(lds + rr * 2048 + cc * 16) = sv[k]; }
.Ldw_incr:
	s_waitcnt vmcnt(8)
	v_mov_b32_e32 v122, v138
	v_mov_b32_e32 v123, v139
	v_mov_b32_e32 v124, v140
	v_mov_b32_e32 v125, v141
	v_mov_b32_e32 v126, v142
	v_mov_b32_e32 v127, v143
	v_mov_b32_e32 v128, v144
	v_mov_b32_e32 v129, v145
	v_mov_b32_e32 v130, v146
	v_mov_b32_e32 v131, v147
	v_mov_b32_e32 v132, v148
	v_mov_b32_e32 v133, v149
	v_mov_b32_e32 v134, v150
	v_mov_b32_e32 v135, v151
	v_mov_b32_e32 v136, v152
	v_mov_b32_e32 v137, v153
	v_mov_b32_e32 v138, v154
	v_mov_b32_e32 v139, v155
	v_mov_b32_e32 v140, v167
	v_mov_b32_e32 v141, v168
	v_mov_b32_e32 v142, v169
	v_mov_b32_e32 v143, v170
	v_mov_b32_e32 v144, v171
	v_mov_b32_e32 v145, v172
	v_mov_b32_e32 v146, v173
	v_mov_b32_e32 v147, v174
	v_mov_b32_e32 v148, v175
	v_mov_b32_e32 v149, v176
	v_mov_b32_e32 v150, v177
	v_mov_b32_e32 v151, v178
	v_mov_b32_e32 v152, v183
	v_mov_b32_e32 v153, v184
	v_mov_b32_e32 v154, v185
	v_mov_b32_e32 v155, v186
	v_mov_b32_e32 v167, v187
	v_mov_b32_e32 v168, v188
	v_mov_b32_e32 v169, v189
	v_mov_b32_e32 v170, v190
	v_mov_b32_e32 v171, v191
	v_mov_b32_e32 v172, v192
	v_mov_b32_e32 v173, v193
	v_mov_b32_e32 v174, v194
	v_mov_b32_e32 v175, v195
	v_mov_b32_e32 v176, v196
	v_mov_b32_e32 v177, v197
	v_mov_b32_e32 v178, v198
